# L2 tile: non-temporal hint on the single-use coefficient, gate and attention-output loads (keeps the re-read chunk aggregates in L2)
# speedup vs baseline: 1.0007x; 1.0007x over previous
.Ll2ci_skip_0_4:
	s_mov_b64 exec, s[26:27]
	s_mov_b64 exec, s[58:59]
	global_load_dwordx4 v[208:211], v100, s[76:77] offset:0
	global_load_dwordx4 v[224:227], v100, s[78:79] offset:0
	global_load_dwordx4 v[212:215], v100, s[76:77] offset:64
	global_load_dwordx4 v[234:237], v100, s[78:79] offset:64
	global_load_dwordx4 v[216:219], v100, s[76:77] offset:128
	global_load_dwordx4 v[246:249], v100, s[78:79] offset:128
	global_load_dwordx4 v[220:223], v100, s[76:77] offset:192
	global_load_dwordx4 v[250:253], v100, s[78:79] offset:192
	s_mov_b64 exec, s[26:27]
	s_nop 4
	v_fmac_f32_dpp v2, v2, v56 row_shr:1 row_mask:0xf bank_mask:0xf bound_ctrl:1
	v_mul_f32_dpp v56, v56, v56 row_shr:1 row_mask:0xf bank_mask:0xf
	v_fmac_f32_dpp v3, v3, v57 row_shr:1 row_mask:0xf bank_mask:0xf bound_ctrl:1
	v_mul_f32_dpp v57, v57, v57 row_shr:1 row_mask:0xf bank_mask:0xf
	v_fmac_f32_dpp v4, v4, v58 row_shr:1 row_mask:0xf bank_mask:0xf bound_ctrl:1
	v_mul_f32_dpp v58, v58, v58 row_shr:1 row_mask:0xf bank_mask:0xf
	v_fmac_f32_dpp v5, v5, v59 row_shr:1 row_mask:0xf bank_mask:0xf bound_ctrl:1
	v_mul_f32_dpp v59, v59, v59 row_shr:1 row_mask:0xf bank_mask:0xf
	v_fmac_f32_dpp v6, v6, v60 row_shr:1 row_mask:0xf bank_mask:0xf bound_ctrl:1
	v_mul_f32_dpp v60, v60, v60 row_shr:1 row_mask:0xf bank_mask:0xf
	v_fmac_f32_dpp v7, v7, v61 row_shr:1 row_mask:0xf bank_mask:0xf bound_ctrl:1
	v_mul_f32_dpp v61, v61, v61 row_shr:1 row_mask:0xf bank_mask:0xf
	v_fmac_f32_dpp v8, v8, v62 row_shr:1 row_mask:0xf bank_mask:0xf bound_ctrl:1
	v_mul_f32_dpp v62, v62, v62 row_shr:1 row_mask:0xf bank_mask:0xf
	v_fmac_f32_dpp v9, v9, v63 row_shr:1 row_mask:0xf bank_mask:0xf bound_ctrl:1
	v_mul_f32_dpp v63, v63, v63 row_shr:1 row_mask:0xf bank_mask:0xf
	v_fmac_f32_dpp v10, v10, v64 row_shr:1 row_mask:0xf bank_mask:0xf bound_ctrl:1
	v_mul_f32_dpp v64, v64, v64 row_shr:1 row_mask:0xf bank_mask:0xf
	v_fmac_f32_dpp v11, v11, v65 row_shr:1 row_mask:0xf bank_mask:0xf bound_ctrl:1
	v_mul_f32_dpp v65, v65, v65 row_shr:1 row_mask:0xf bank_mask:0xf
	v_fmac_f32_dpp v12, v12, v66 row_shr:1 row_mask:0xf bank_mask:0xf bound_ctrl:1
	v_mul_f32_dpp v66, v66, v66 row_shr:1 row_mask:0xf bank_mask:0xf
	v_fmac_f32_dpp v13, v13, v67 row_shr:1 row_mask:0xf bank_mask:0xf bound_ctrl:1
	v_mul_f32_dpp v67, v67, v67 row_shr:1 row_mask:0xf bank_mask:0xf
	v_fmac_f32_dpp v14, v14, v68 row_shr:1 row_mask:0xf bank_mask:0xf bound_ctrl:1
	v_mul_f32_dpp v68, v68, v68 row_shr:1 row_mask:0xf bank_mask:0xf
	v_fmac_f32_dpp v15, v15, v69 row_shr:1 row_mask:0xf bank_mask:0xf bound_ctrl:1
	v_mul_f32_dpp v69, v69, v69 row_shr:1 row_mask:0xf bank_mask:0xf
	v_fmac_f32_dpp v16, v16, v70 row_shr:1 row_mask:0xf bank_mask:0xf bound_ctrl:1
	v_mul_f32_dpp v70, v70, v70 row_shr:1 row_mask:0xf bank_mask:0xf
	v_fmac_f32_dpp v17, v17, v71 row_shr:1 row_mask:0xf bank_mask:0xf bound_ctrl:1
	v_mul_f32_dpp v71, v71, v71 row_shr:1 row_mask:0xf bank_mask:0xf
	v_fmac_f32_dpp v2, v2, v56 row_shr:2 row_mask:0xf bank_mask:0xf bound_ctrl:1
	v_mul_f32_dpp v56, v56, v56 row_shr:2 row_mask:0xf bank_mask:0xf
	v_fmac_f32_dpp v3, v3, v57 row_shr:2 row_mask:0xf bank_mask:0xf bound_ctrl:1
	v_mul_f32_dpp v57, v57, v57 row_shr:2 row_mask:0xf bank_mask:0xf
	v_fmac_f32_dpp v4, v4, v58 row_shr:2 row_mask:0xf bank_mask:0xf bound_ctrl:1
	v_mul_f32_dpp v58, v58, v58 row_shr:2 row_mask:0xf bank_mask:0xf
	v_fmac_f32_dpp v5, v5, v59 row_shr:2 row_mask:0xf bank_mask:0xf bound_ctrl:1
	v_mul_f32_dpp v59, v59, v59 row_shr:2 row_mask:0xf bank_mask:0xf
	v_fmac_f32_dpp v6, v6, v60 row_shr:2 row_mask:0xf bank_mask:0xf bound_ctrl:1
	v_mul_f32_dpp v60, v60, v60 row_shr:2 row_mask:0xf bank_mask:0xf
	v_fmac_f32_dpp v7, v7, v61 row_shr:2 row_mask:0xf bank_mask:0xf bound_ctrl:1
	v_mul_f32_dpp v61, v61, v61 row_shr:2 row_mask:0xf bank_mask:0xf
	v_fmac_f32_dpp v8, v8, v62 row_shr:2 row_mask:0xf bank_mask:0xf bound_ctrl:1
	v_mul_f32_dpp v62, v62, v62 row_shr:2 row_mask:0xf bank_mask:0xf
	v_fmac_f32_dpp v9, v9, v63 row_shr:2 row_mask:0xf bank_mask:0xf bound_ctrl:1
	v_mul_f32_dpp v63, v63, v63 row_shr:2 row_mask:0xf bank_mask:0xf
	v_fmac_f32_dpp v10, v10, v64 row_shr:2 row_mask:0xf bank_mask:0xf bound_ctrl:1
	v_mul_f32_dpp v64, v64, v64 row_shr:2 row_mask:0xf bank_mask:0xf
	v_fmac_f32_dpp v11, v11, v65 row_shr:2 row_mask:0xf bank_mask:0xf bound_ctrl:1
	v_mul_f32_dpp v65, v65, v65 row_shr:2 row_mask:0xf bank_mask:0xf
	v_fmac_f32_dpp v12, v12, v66 row_shr:2 row_mask:0xf bank_mask:0xf bound_ctrl:1
	v_mul_f32_dpp v66, v66, v66 row_shr:2 row_mask:0xf bank_mask:0xf
	v_fmac_f32_dpp v13, v13, v67 row_shr:2 row_mask:0xf bank_mask:0xf bound_ctrl:1
	v_mul_f32_dpp v67, v67, v67 row_shr:2 row_mask:0xf bank_mask:0xf
	v_fmac_f32_dpp v14, v14, v68 row_shr:2 row_mask:0xf bank_mask:0xf bound_ctrl:1
	v_mul_f32_dpp v68, v68, v68 row_shr:2 row_mask:0xf bank_mask:0xf
	v_fmac_f32_dpp v15, v15, v69 row_shr:2 row_mask:0xf bank_mask:0xf bound_ctrl:1
	v_mul_f32_dpp v69, v69, v69 row_shr:2 row_mask:0xf bank_mask:0xf
	v_fmac_f32_dpp v16, v16, v70 row_shr:2 row_mask:0xf bank_mask:0xf bound_ctrl:1
	v_mul_f32_dpp v70, v70, v70 row_shr:2 row_mask:0xf bank_mask:0xf
	v_fmac_f32_dpp v17, v17, v71 row_shr:2 row_mask:0xf bank_mask:0xf bound_ctrl:1
	v_mul_f32_dpp v71, v71, v71 row_shr:2 row_mask:0xf bank_mask:0xf
	v_fmac_f32_dpp v2, v2, v56 row_shr:4 row_mask:0xf bank_mask:0xf bound_ctrl:1
	v_mul_f32_dpp v56, v56, v56 row_shr:4 row_mask:0xf bank_mask:0xf
	v_fmac_f32_dpp v3, v3, v57 row_shr:4 row_mask:0xf bank_mask:0xf bound_ctrl:1
	v_mul_f32_dpp v57, v57, v57 row_shr:4 row_mask:0xf bank_mask:0xf
	v_fmac_f32_dpp v4, v4, v58 row_shr:4 row_mask:0xf bank_mask:0xf bound_ctrl:1
	v_mul_f32_dpp v58, v58, v58 row_shr:4 row_mask:0xf bank_mask:0xf
	v_fmac_f32_dpp v5, v5, v59 row_shr:4 row_mask:0xf bank_mask:0xf bound_ctrl:1
	v_mul_f32_dpp v59, v59, v59 row_shr:4 row_mask:0xf bank_mask:0xf
	v_fmac_f32_dpp v6, v6, v60 row_shr:4 row_mask:0xf bank_mask:0xf bound_ctrl:1
	v_mul_f32_dpp v60, v60, v60 row_shr:4 row_mask:0xf bank_mask:0xf
	v_fmac_f32_dpp v7, v7, v61 row_shr:4 row_mask:0xf bank_mask:0xf bound_ctrl:1
	v_mul_f32_dpp v61, v61, v61 row_shr:4 row_mask:0xf bank_mask:0xf
	v_fmac_f32_dpp v8, v8, v62 row_shr:4 row_mask:0xf bank_mask:0xf bound_ctrl:1
	v_mul_f32_dpp v62, v62, v62 row_shr:4 row_mask:0xf bank_mask:0xf
	v_fmac_f32_dpp v9, v9, v63 row_shr:4 row_mask:0xf bank_mask:0xf bound_ctrl:1
	v_mul_f32_dpp v63, v63, v63 row_shr:4 row_mask:0xf bank_mask:0xf
	v_fmac_f32_dpp v10, v10, v64 row_shr:4 row_mask:0xf bank_mask:0xf bound_ctrl:1
	v_mul_f32_dpp v64, v64, v64 row_shr:4 row_mask:0xf bank_mask:0xf
	v_fmac_f32_dpp v11, v11, v65 row_shr:4 row_mask:0xf bank_mask:0xf bound_ctrl:1
	v_mul_f32_dpp v65, v65, v65 row_shr:4 row_mask:0xf bank_mask:0xf
	v_fmac_f32_dpp v12, v12, v66 row_shr:4 row_mask:0xf bank_mask:0xf bound_ctrl:1
	v_mul_f32_dpp v66, v66, v66 row_shr:4 row_mask:0xf bank_mask:0xf
	v_fmac_f32_dpp v13, v13, v67 row_shr:4 row_mask:0xf bank_mask:0xf bound_ctrl:1
	v_mul_f32_dpp v67, v67, v67 row_shr:4 row_mask:0xf bank_mask:0xf
	v_fmac_f32_dpp v14, v14, v68 row_shr:4 row_mask:0xf bank_mask:0xf bound_ctrl:1
	v_mul_f32_dpp v68, v68, v68 row_shr:4 row_mask:0xf bank_mask:0xf
	v_fmac_f32_dpp v15, v15, v69 row_shr:4 row_mask:0xf bank_mask:0xf bound_ctrl:1
	v_mul_f32_dpp v69, v69, v69 row_shr:4 row_mask:0xf bank_mask:0xf
	v_fmac_f32_dpp v16, v16, v70 row_shr:4 row_mask:0xf bank_mask:0xf bound_ctrl:1
	v_mul_f32_dpp v70, v70, v70 row_shr:4 row_mask:0xf bank_mask:0xf
	v_fmac_f32_dpp v17, v17, v71 row_shr:4 row_mask:0xf bank_mask:0xf bound_ctrl:1
	v_mul_f32_dpp v71, v71, v71 row_shr:4 row_mask:0xf bank_mask:0xf
	v_fmac_f32_dpp v2, v2, v56 row_shr:8 row_mask:0xf bank_mask:0xf bound_ctrl:1
	v_fmac_f32_dpp v3, v3, v57 row_shr:8 row_mask:0xf bank_mask:0xf bound_ctrl:1
	v_fmac_f32_dpp v4, v4, v58 row_shr:8 row_mask:0xf bank_mask:0xf bound_ctrl:1
	v_fmac_f32_dpp v5, v5, v59 row_shr:8 row_mask:0xf bank_mask:0xf bound_ctrl:1
	v_fmac_f32_dpp v6, v6, v60 row_shr:8 row_mask:0xf bank_mask:0xf bound_ctrl:1
	v_fmac_f32_dpp v7, v7, v61 row_shr:8 row_mask:0xf bank_mask:0xf bound_ctrl:1
	v_fmac_f32_dpp v8, v8, v62 row_shr:8 row_mask:0xf bank_mask:0xf bound_ctrl:1
	v_fmac_f32_dpp v9, v9, v63 row_shr:8 row_mask:0xf bank_mask:0xf bound_ctrl:1
	v_fmac_f32_dpp v10, v10, v64 row_shr:8 row_mask:0xf bank_mask:0xf bound_ctrl:1
	v_fmac_f32_dpp v11, v11, v65 row_shr:8 row_mask:0xf bank_mask:0xf bound_ctrl:1
	v_fmac_f32_dpp v12, v12, v66 row_shr:8 row_mask:0xf bank_mask:0xf bound_ctrl:1
	v_fmac_f32_dpp v13, v13, v67 row_shr:8 row_mask:0xf bank_mask:0xf bound_ctrl:1
	v_fmac_f32_dpp v14, v14, v68 row_shr:8 row_mask:0xf bank_mask:0xf bound_ctrl:1
	v_fmac_f32_dpp v15, v15, v69 row_shr:8 row_mask:0xf bank_mask:0xf bound_ctrl:1
	v_fmac_f32_dpp v16, v16, v70 row_shr:8 row_mask:0xf bank_mask:0xf bound_ctrl:1
	v_fmac_f32_dpp v17, v17, v71 row_shr:8 row_mask:0xf bank_mask:0xf bound_ctrl:1
	s_nop 1
	ds_bpermute_b32 v34, v245, v2
	ds_bpermute_b32 v35, v245, v3
	ds_bpermute_b32 v32, v245, v4
	ds_bpermute_b32 v33, v245, v5
	ds_bpermute_b32 v30, v245, v6
	ds_bpermute_b32 v31, v245, v7
	ds_bpermute_b32 v28, v245, v8
	ds_bpermute_b32 v29, v245, v9
	ds_bpermute_b32 v26, v245, v10
	ds_bpermute_b32 v27, v245, v11
	ds_bpermute_b32 v24, v245, v12
	ds_bpermute_b32 v25, v245, v13
	ds_bpermute_b32 v22, v245, v14
	ds_bpermute_b32 v23, v245, v15
	ds_bpermute_b32 v20, v245, v16
	ds_bpermute_b32 v21, v245, v17
	s_waitcnt vmcnt(32)
	v_cndmask_b32_e64 v56, 1.0, v36, s[18:19]
	v_cndmask_b32_e64 v2, 0, v84, s[18:19]
	v_cndmask_b32_e64 v57, 1.0, v37, s[18:19]
	v_cndmask_b32_e64 v3, 0, v85, s[18:19]
	v_cndmask_b32_e64 v58, 1.0, v38, s[18:19]
	v_cndmask_b32_e64 v4, 0, v86, s[18:19]
	v_cndmask_b32_e64 v59, 1.0, v39, s[18:19]
	v_cndmask_b32_e64 v5, 0, v87, s[18:19]
	v_cndmask_b32_e64 v60, 1.0, v40, s[18:19]
	v_cndmask_b32_e64 v6, 0, v88, s[18:19]
	v_cndmask_b32_e64 v61, 1.0, v41, s[18:19]
	v_cndmask_b32_e64 v7, 0, v89, s[18:19]
	v_cndmask_b32_e64 v62, 1.0, v42, s[18:19]
	v_cndmask_b32_e64 v8, 0, v90, s[18:19]
	v_cndmask_b32_e64 v63, 1.0, v43, s[18:19]
	v_cndmask_b32_e64 v9, 0, v91, s[18:19]
	v_cndmask_b32_e64 v64, 1.0, v44, s[18:19]
	v_cndmask_b32_e64 v10, 0, v102, s[18:19]
	v_cndmask_b32_e64 v65, 1.0, v45, s[18:19]
	v_cndmask_b32_e64 v11, 0, v103, s[18:19]
	v_cndmask_b32_e64 v66, 1.0, v46, s[18:19]
	v_cndmask_b32_e64 v12, 0, v104, s[18:19]
	v_cndmask_b32_e64 v67, 1.0, v47, s[18:19]
	v_cndmask_b32_e64 v13, 0, v105, s[18:19]
	v_cndmask_b32_e64 v68, 1.0, v48, s[18:19]
	v_cndmask_b32_e64 v14, 0, v106, s[18:19]
	v_cndmask_b32_e64 v69, 1.0, v49, s[18:19]
	v_cndmask_b32_e64 v15, 0, v107, s[18:19]
	v_cndmask_b32_e64 v70, 1.0, v50, s[18:19]
	v_cndmask_b32_e64 v16, 0, v108, s[18:19]
	v_cndmask_b32_e64 v71, 1.0, v51, s[18:19]
	v_cndmask_b32_e64 v17, 0, v109, s[18:19]
	s_lshl_b32 s10, s48, 6
	s_add_i32 s11, s10, 0xffffff00
	s_and_b64 s[8:9], s[6:7], exec
	s_cselect_b32 s8, s11, s10
	s_lshl_b32 s9, s40, 8
	s_addk_i32 s9, 0x4000
	s_lshl_b32 s10, s40, 12
	s_and_b64 s[6:7], s[6:7], exec
	s_cselect_b32 s10, s10, s9
	s_add_i32 s10, s10, s8
	s_ashr_i32 s6, s10, 4
	s_ashr_i32 s7, s6, 31
	s_lshl_b64 s[8:9], s[6:7], 14
	s_add_u32 s8, s4, s8
	s_addc_u32 s9, s5, s9
	s_lshl_b64 s[6:7], s[6:7], 15
	v_lshlrev_b32_e32 v0, 5, v101
	s_add_u32 s6, s30, s6
	v_lshl_add_u64 v[54:55], s[8:9], 0, v[0:1]
	s_addc_u32 s7, s31, s7
	v_lshlrev_b32_e32 v0, 6, v101
	v_lshl_add_u64 v[94:95], s[6:7], 0, v[0:1]
	v_lshl_add_u64 v[52:53], v[18:19], 2, v[94:95]
	global_load_dwordx4 v[84:87], v[52:53], off nt
	global_load_dwordx4 v[88:91], v[52:53], off offset:1024 nt
	global_load_dwordx4 v[102:105], v[52:53], off offset:2048 nt
	global_load_dwordx4 v[106:109], v[52:53], off offset:3072 nt
	s_waitcnt vmcnt(28)
	s_mov_b64 exec, s[20:21]
	s_cbranch_execz .Ll2ci_skip_1_1
	v_pk_fma_f32 v[2:3], v[110:111], v[2:3], v[126:127]
	v_pk_mul_f32 v[56:57], v[56:57], v[110:111]
	v_pk_fma_f32 v[4:5], v[112:113], v[4:5], v[128:129]
	v_pk_mul_f32 v[58:59], v[58:59], v[112:113]
	v_pk_fma_f32 v[6:7], v[114:115], v[6:7], v[130:131]
	v_pk_mul_f32 v[60:61], v[60:61], v[114:115]
	v_pk_fma_f32 v[8:9], v[116:117], v[8:9], v[132:133]
	v_pk_mul_f32 v[62:63], v[62:63], v[116:117]
	v_pk_fma_f32 v[10:11], v[118:119], v[10:11], v[134:135]
	v_pk_mul_f32 v[64:65], v[64:65], v[118:119]
	v_pk_fma_f32 v[12:13], v[120:121], v[12:13], v[136:137]
	v_pk_mul_f32 v[66:67], v[66:67], v[120:121]
	v_pk_fma_f32 v[14:15], v[122:123], v[14:15], v[138:139]
	v_pk_mul_f32 v[68:69], v[68:69], v[122:123]
	v_pk_fma_f32 v[16:17], v[124:125], v[16:17], v[140:141]
	v_pk_mul_f32 v[70:71], v[70:71], v[124:125]

.Ll2_step:
	s_add_i32 s12, s14, 1
	s_cmp_lg_u32 s14, 7
	s_cselect_b32 s9, s12, 7
	s_sub_i32 s8, 7, s9
	s_cmp_lt_u32 s9, 4
	s_cselect_b32 s8, s9, s8
	s_cmp_gt_u32 s9, 3
	s_cselect_b32 s74, 0x2200000, 0
	s_ashr_i32 s9, s8, 31
	s_lshl_b64 s[16:17], s[8:9], 15
	s_lshl_b64 s[8:9], s[8:9], 14
	v_lshl_add_u64 v[84:85], v[52:53], 0, s[74:75]
	v_lshl_add_u64 v[86:87], v[54:55], 0, s[8:9]
	v_lshl_add_u64 v[84:85], v[84:85], 0, s[16:17]
	s_cmp_lt_u32 s14, 4
	s_cselect_b32 s8, s14, s11
	s_lshl_b32 s13, s8, 12
	v_add_u32_e32 v81, s13, v125
	s_waitcnt vmcnt(0)
	v_cvt_f32_f16_e32 v130, v2
	v_cvt_f32_f16_sdwa v146, v2 dst_sel:DWORD dst_unused:UNUSED_PAD src0_sel:WORD_1
	v_cvt_f32_f16_e32 v131, v3
	v_cvt_f32_f16_sdwa v147, v3 dst_sel:DWORD dst_unused:UNUSED_PAD src0_sel:WORD_1
	v_cvt_f32_f16_e32 v132, v4
	v_cvt_f32_f16_sdwa v148, v4 dst_sel:DWORD dst_unused:UNUSED_PAD src0_sel:WORD_1
	v_cvt_f32_f16_e32 v133, v5
	v_cvt_f32_f16_sdwa v149, v5 dst_sel:DWORD dst_unused:UNUSED_PAD src0_sel:WORD_1
	v_cvt_f32_f16_e32 v134, v6
	v_cvt_f32_f16_sdwa v150, v6 dst_sel:DWORD dst_unused:UNUSED_PAD src0_sel:WORD_1
	v_cvt_f32_f16_e32 v135, v7
	v_cvt_f32_f16_sdwa v151, v7 dst_sel:DWORD dst_unused:UNUSED_PAD src0_sel:WORD_1
	v_cvt_f32_f16_e32 v136, v8
	v_cvt_f32_f16_sdwa v152, v8 dst_sel:DWORD dst_unused:UNUSED_PAD src0_sel:WORD_1
	v_cvt_f32_f16_e32 v137, v9
	v_cvt_f32_f16_sdwa v153, v9 dst_sel:DWORD dst_unused:UNUSED_PAD src0_sel:WORD_1
	v_cvt_f32_f16_e32 v138, v10
	v_cvt_f32_f16_sdwa v154, v10 dst_sel:DWORD dst_unused:UNUSED_PAD src0_sel:WORD_1
	v_cvt_f32_f16_e32 v139, v11
	v_cvt_f32_f16_sdwa v155, v11 dst_sel:DWORD dst_unused:UNUSED_PAD src0_sel:WORD_1
	v_cvt_f32_f16_e32 v140, v12
	v_cvt_f32_f16_sdwa v156, v12 dst_sel:DWORD dst_unused:UNUSED_PAD src0_sel:WORD_1
	v_cvt_f32_f16_e32 v141, v13
	v_cvt_f32_f16_sdwa v157, v13 dst_sel:DWORD dst_unused:UNUSED_PAD src0_sel:WORD_1
	v_cvt_f32_f16_e32 v142, v14
	v_cvt_f32_f16_sdwa v158, v14 dst_sel:DWORD dst_unused:UNUSED_PAD src0_sel:WORD_1
	v_cvt_f32_f16_e32 v143, v15
	v_cvt_f32_f16_sdwa v159, v15 dst_sel:DWORD dst_unused:UNUSED_PAD src0_sel:WORD_1
	v_cvt_f32_f16_e32 v144, v16
	v_cvt_f32_f16_sdwa v160, v16 dst_sel:DWORD dst_unused:UNUSED_PAD src0_sel:WORD_1
	v_cvt_f32_f16_e32 v145, v17
	v_cvt_f32_f16_sdwa v161, v17 dst_sel:DWORD dst_unused:UNUSED_PAD src0_sel:WORD_1
	v_lshlrev_b32_e32 v162, 16, v56
	v_and_b32_e32 v163, 0xffff0000, v56
	v_lshlrev_b32_e32 v164, 16, v57
	v_and_b32_e32 v165, 0xffff0000, v57
	v_lshlrev_b32_e32 v166, 16, v58
	v_and_b32_e32 v167, 0xffff0000, v58
	v_lshlrev_b32_e32 v168, 16, v59
	v_and_b32_e32 v169, 0xffff0000, v59
	v_lshlrev_b32_e32 v170, 16, v60
	v_and_b32_e32 v171, 0xffff0000, v60
	v_lshlrev_b32_e32 v172, 16, v61
	v_and_b32_e32 v173, 0xffff0000, v61
	v_lshlrev_b32_e32 v174, 16, v62
	v_and_b32_e32 v175, 0xffff0000, v62
	v_lshlrev_b32_e32 v176, 16, v63
	v_and_b32_e32 v177, 0xffff0000, v63
	s_cmp_eq_u32 s14, 7
	s_cbranch_scc1 .Ll2_noload
	global_load_dwordx4 v[2:5], v[84:85], off nt
	global_load_dwordx4 v[6:9], v[84:85], off offset:1024 nt
	global_load_dwordx4 v[10:13], v[84:85], off offset:2048 nt
	global_load_dwordx4 v[14:17], v[84:85], off offset:3072 nt
	global_load_dwordx2 v[56:57], v[86:87], off nt
	global_load_dwordx2 v[58:59], v[86:87], off offset:512 nt
	global_load_dwordx2 v[60:61], v[86:87], off offset:1024 nt
	global_load_dwordx2 v[62:63], v[86:87], off offset:1536 nt

.Ll2_tail:
	s_add_i32 s11, s11, -1
	v_subrev_u32_e32 v126, 64, v126
	s_cmp_eq_u32 s12, 8
	s_mov_b32 s14, s12
	s_cbranch_scc0 .Ll2_step
	s_waitcnt vmcnt(0)
	s_add_i32 s26, s10, s43
	s_ashr_i32 s27, s26, 31
	s_lshl_b64 s[28:29], s[26:27], 10
	v_readlane_b32 s76, v255, 54
	v_readlane_b32 s77, v255, 55
	v_lshrrev_b32_e32 v162, 4, v228
	v_and_b32_e32 v163, 15, v228
	v_lshlrev_b32_e32 v163, 4, v163
	s_add_u32 s76, s76, s28
	s_addc_u32 s77, s77, s29
	v_lshl_add_u32 v162, v162, 10, v163
	v_add_u32_e32 v163, 0x1000, v162
	global_load_dwordx4 v[130:133], v162, s[76:77] nt
	global_load_dwordx4 v[134:137], v162, s[76:77] offset:256 nt
	global_load_dwordx4 v[138:141], v162, s[76:77] offset:512 nt
	global_load_dwordx4 v[142:145], v162, s[76:77] offset:768 nt
	global_load_dwordx4 v[146:149], v163, s[76:77] nt
	global_load_dwordx4 v[150:153], v163, s[76:77] offset:256 nt
	global_load_dwordx4 v[154:157], v163, s[76:77] offset:512 nt
	global_load_dwordx4 v[158:161], v163, s[76:77] offset:768 nt
